# conversion items rebalanced: 3072 fewer in the idle half-round of the even in-proj GEMM (its conversion was that phase's tail), converted in the MLA attention phase instead
# baseline (speedup 1.0000x reference)
.LBB0_546:
	s_cmpk_lg_i32 s62, 0x100
	s_cselect_b64 s[6:7], -1, 0
	s_cmpk_lt_i32 s92, 0x80
	s_cselect_b64 s[8:9], -1, 0
	s_or_b64 s[6:7], s[6:7], s[8:9]
	s_cmpk_gt_u32 s90, 0xff
	s_cselect_b64 s[8:9], -1, 0
	s_or_b64 s[6:7], s[6:7], s[8:9]
	s_and_b64 vcc, exec, s[6:7]
	s_cbranch_vccnz .LBB0_601
	s_lshl_b32 s3, s92, 2
	s_add_i32 s3, s3, s33
	s_addk_i32 s3, 0x1020
	s_cmpk_gt_i32 s3, 0x2e1f
	s_cbranch_scc1 .LBB0_601
	s_load_dwordx2 s[30:31], s[0:1], 0xf0
	s_load_dwordx2 s[6:7], s[0:1], 0xa0
	s_load_dwordx2 s[20:21], s[0:1], 0x50
	s_load_dwordx4 s[8:11], s[0:1], 0x68
	s_waitcnt lgkmcnt(0)
	s_load_dwordx2 s[22:23], s[0:1], 0x78
	s_load_dwordx4 s[12:15], s[0:1], 0x88
	v_and_b32_e32 v4, 63, v152
	v_lshlrev_b32_e32 v5, 2, v4
	s_add_u32 s52, s30, 0x33d8000
	s_addc_u32 s53, s31, 0
	s_add_u32 s54, s30, 0x233d8000
	s_addc_u32 s55, s31, 0
	s_add_u32 s18, s30, 0x2bd8000
	s_addc_u32 s19, s31, 0
	s_add_u32 s24, s30, 0x21d8000
	s_addc_u32 s25, s31, 0
	s_add_u32 s26, s30, 0x19d8000
	s_addc_u32 s27, s31, 0
	s_add_u32 s28, s30, 0xa18000
	s_addc_u32 s29, s31, 0
	s_add_u32 s30, s30, 0x218000
	s_addc_u32 s31, s31, 0
	s_lshl_b32 s34, s3, 8
	v_and_b32_e32 v6, 0x7c, v5
	s_add_i32 s63, s34, 0xfff1e000
	s_mov_b32 s35, 0
	v_mov_b32_e32 v1, 0
	s_movk_i32 s66, 0x2000
	s_movk_i32 s67, 0x4000
	s_movk_i32 s68, 0x6000
	s_mov_b32 s69, 0x8000
	s_mov_b32 s70, 0xa000
	s_mov_b32 s71, 0xc000
	s_mov_b32 s72, 0xe000
	s_mov_b32 s73, 0x10000
	s_mov_b32 s74, 0x12000
	s_mov_b32 s75, 0x14000
	s_mov_b32 s76, 0x16000
	s_mov_b32 s77, 0x18000
	s_mov_b32 s78, 0x1a000
	s_mov_b32 s79, 0x1c000
	s_mov_b32 s80, 0x1e000
	s_movk_i32 s81, 0x7f
	s_movk_i32 s82, 0x2ff
	s_branch .LBB0_551

.LBB0_550:
	s_add_i32 s34, s3, 0x200
	s_add_i32 s63, s63, 0x20000
	s_cmpk_lt_i32 s3, 0x2c20
	s_mov_b32 s3, s34
	s_cbranch_scc0 .LBB0_601

.LBB0_1133:
	s_andn2_b64 vcc, exec, s[6:7]
	s_cbranch_vccnz .LBB0_1209
	s_load_dwordx2 s[22:23], s[0:1], 0xf0
	s_and_b32 s6, s90, 0xffffffc0
	v_mbcnt_hi_u32_b32 v51, -1, v254
	v_mov_b32_e32 v52, v51
	s_waitcnt lgkmcnt(0)
	s_add_u32 s3, s22, 0x421d8000
	s_addc_u32 s52, s23, 0
	s_add_u32 s24, s22, 0x3efd8000
	s_addc_u32 s25, s23, 0
	s_add_u32 s26, s22, 0x441d8000
	s_addc_u32 s27, s23, 0
	s_cmpk_gt_u32 s90, 0xff
	v_add_u32_e32 v50, s6, v52
	v_and_b32_e32 v53, 63, v52
	s_mov_b64 s[6:7], -1
	s_cbranch_scc0 .LBB0_1178
	s_lshl_b32 s6, s92, 2
	s_add_i32 s6, s6, s33
	s_add_i32 s53, s6, 0x1bfc
	s_mov_b32 s99, 0
	s_cmpk_gt_i32 s92, 0x2ff
	v_lshlrev_b32_e32 v54, 2, v53
	s_cbranch_scc1 .LBB0_1169
	v_lshlrev_b32_e32 v0, 4, v52
	s_mov_b32 s14, 0x2aaaaaab
	v_and_b32_e32 v20, 0x70, v0
	v_mul_hi_i32 v0, v50, s14
	v_lshrrev_b32_e32 v1, 31, v0
	v_ashrrev_i32_e32 v0, 2, v0
	v_add_u32_e32 v56, v0, v1
	v_add_u32_e32 v1, 0x200, v50
	v_mul_hi_i32 v2, v1, s14
	v_lshrrev_b32_e32 v3, 31, v2
	v_ashrrev_i32_e32 v2, 2, v2
	v_add_u32_e32 v57, v2, v3
	v_add_u32_e32 v3, 0x400, v50
	v_mul_hi_i32 v4, v3, s14
	v_mul_lo_u32 v0, v56, 24
	v_lshrrev_b32_e32 v5, 31, v4
	v_ashrrev_i32_e32 v4, 2, v4
	v_sub_u32_e32 v0, v50, v0
	v_mul_lo_u32 v2, v57, 24
	v_add_u32_e32 v58, v4, v5
	v_mov_b32_e32 v23, 0
	v_lshlrev_b32_e32 v22, 3, v0
	v_sub_u32_e32 v2, v1, v2
	v_mul_lo_u32 v4, v58, 24
	s_movk_i32 s20, 0x190
	s_add_u32 s48, s22, 0x33d8000
	v_lshl_add_u64 v[26:27], v[22:23], 1, s[24:25]
	v_ashrrev_i32_e32 v29, 31, v22
	v_mov_b32_e32 v28, v22
	v_lshlrev_b32_e32 v22, 3, v2
	v_sub_u32_e32 v3, v3, v4
	v_mul_lo_u32 v61, v56, s20
	v_mul_lo_u32 v63, v57, s20
	v_mul_lo_u32 v65, v58, s20
	s_addc_u32 s49, s23, 0
	v_mov_b32_e32 v21, v23
	v_cmp_gt_i32_e64 s[6:7], 16, v0
	v_cmp_lt_i32_e64 s[8:9], 15, v0
	v_cmp_gt_i32_e64 s[10:11], 16, v2
	v_cmp_lt_i32_e64 s[12:13], 15, v2
	v_lshl_add_u64 v[30:31], v[22:23], 1, s[24:25]
	v_ashrrev_i32_e32 v33, 31, v22
	v_mov_b32_e32 v32, v22
	v_lshlrev_b32_e32 v22, 3, v3
	v_ashrrev_i32_e32 v59, 3, v50
	v_ashrrev_i32_e32 v60, 3, v1
	v_add_u32_e32 v1, 0, v61
	v_lshlrev_b32_e32 v62, 4, v0
	v_add_u32_e32 v0, 0, v63
	v_lshlrev_b32_e32 v64, 4, v2
	v_add_u32_e32 v2, 0, v65
	v_lshlrev_b32_e32 v66, 4, v3
	s_movk_i32 s20, 0x88
	s_add_u32 s54, s22, 0x233d8000
	s_movk_i32 s28, 0xff00
	v_lshl_add_u64 v[24:25], s[26:27], 0, v[20:21]
	s_mov_b32 s21, 0
	v_add_u32_e32 v21, 0, v20
	v_and_b32_e32 v55, 0x7c, v54
	v_cmp_gt_i32_e64 s[14:15], 16, v3
	v_cmp_lt_i32_e64 s[16:17], 15, v3
	v_lshl_add_u64 v[34:35], v[22:23], 1, s[24:25]
	v_ashrrev_i32_e32 v37, 31, v22
	v_mov_b32_e32 v36, v22
	v_mul_lo_u32 v67, v59, s20
	v_mul_lo_u32 v68, v60, s20
	s_addc_u32 s55, s23, 0
	s_mov_b32 s29, -1
	v_add_u32_e32 v69, v1, v62
	v_add_u32_e32 v70, v0, v64
	v_add_u32_e32 v71, v2, v66
	s_movk_i32 s63, 0x6400
	s_movk_i32 s64, 0x2000
	s_movk_i32 s65, 0x4000
	s_movk_i32 s66, 0x6000
	s_mov_b32 s67, 0x8000
	s_mov_b32 s68, 0xa000
	s_mov_b32 s69, 0xc000
	s_mov_b32 s70, 0xe000
	s_mov_b32 s71, 0x10000
	s_mov_b32 s72, 0x12000
	s_mov_b32 s73, 0x14000
	s_mov_b32 s74, 0x16000
	s_mov_b32 s75, 0x18000
	s_mov_b32 s76, 0x1a000
	s_mov_b32 s77, 0x1c000
	s_mov_b32 s78, 0x1e000
	s_mov_b32 s79, s92
	s_branch .LBB0_1138
